# attention: first four V fragment reads issued ahead of the row-max chain
# speedup vs baseline: 1.0097x; 1.0097x over previous
.Latt_nodma:
	v_add_u32_e32 v8, s27, v210
	v_add_u32_e32 v42, v8, v215
	v_add_u32_e32 v43, v8, v216
	ds_read_b128 v[16:19], v42 offset:0
	ds_read_b128 v[20:23], v42 offset:2048
	ds_read_b128 v[24:27], v42 offset:4096
	ds_read_b128 v[28:31], v42 offset:6144
	v_max3_f32 v36, v140, v141, v142
	v_max3_f32 v37, v124, v125, v126
	v_max3_f32 v36, v36, v143, v144
	v_max3_f32 v37, v37, v127, v128
	v_max3_f32 v36, v36, v145, v146
	v_max3_f32 v37, v37, v129, v130
	v_max3_f32 v36, v36, v147, v148
	v_max3_f32 v37, v37, v131, v132
	v_max3_f32 v36, v36, v149, v150
	v_max3_f32 v37, v37, v133, v134
	v_max3_f32 v36, v36, v151, v152
	v_max3_f32 v37, v37, v135, v136
	v_max3_f32 v36, v36, v153, v154
	v_max3_f32 v37, v37, v137, v138
	v_max3_f32 v36, v36, v155, v155
	v_max3_f32 v37, v37, v139, v139
	v_max_f32_e32 v9, v36, v37
	v_cmp_lt_f32_e32 vcc, s44, v9
	ds_read_b128 v[188:191], v43 offset:0
	ds_read_b128 v[192:195], v43 offset:2048
	ds_read_b128 v[196:199], v43 offset:4096
	ds_read_b128 v[32:35], v43 offset:6144
	s_cmp_eq_u32 s11, 0
	s_cbranch_scc1 .Latt_rare_a
	s_cbranch_vccnz .Latt_rare_a
.Latt_c_a:
	v_exp_f32_e32 v140, v140
	v_exp_f32_e32 v141, v141
	v_exp_f32_e32 v142, v142
	v_exp_f32_e32 v143, v143
	v_exp_f32_e32 v144, v144
	v_exp_f32_e32 v145, v145
	v_exp_f32_e32 v146, v146
	v_exp_f32_e32 v147, v147
	v_exp_f32_e32 v124, v124
	v_exp_f32_e32 v125, v125
	v_exp_f32_e32 v126, v126
	v_exp_f32_e32 v127, v127
	v_exp_f32_e32 v128, v128
	v_exp_f32_e32 v129, v129
	v_exp_f32_e32 v130, v130
	v_exp_f32_e32 v131, v131
	v_cvt_pk_bf16_f32 v140, v140, v141
	v_cvt_pk_bf16_f32 v141, v142, v143
	v_cvt_pk_bf16_f32 v142, v144, v145
	v_cvt_pk_bf16_f32 v143, v146, v147
	v_cvt_pk_bf16_f32 v124, v124, v125
	v_cvt_pk_bf16_f32 v125, v126, v127
	v_cvt_pk_bf16_f32 v126, v128, v129
	v_cvt_pk_bf16_f32 v127, v130, v131
	s_waitcnt lgkmcnt(4)
	ds_read_b128 v[156:159], v38 offset:16384
	ds_read_b128 v[160:163], v38 offset:20480
	ds_read_b128 v[164:167], v38 offset:24576
	ds_read_b128 v[168:171], v38 offset:28672
	ds_read_b128 v[172:175], v39 offset:16384
	ds_read_b128 v[176:179], v39 offset:20480
	ds_read_b128 v[180:183], v39 offset:24576
	ds_read_b128 v[184:187], v39 offset:28672
	s_setprio 1
	s_waitcnt lgkmcnt(12)
	v_mfma_f32_16x16x32_bf16 v[92:95], v[16:19], v[140:143], v[92:95]
	v_exp_f32_e32 v148, v148
	v_exp_f32_e32 v149, v149
	v_mfma_f32_16x16x32_bf16 v[96:99], v[16:19], v[124:127], v[96:99]
	v_exp_f32_e32 v150, v150
	v_exp_f32_e32 v151, v151
	v_mfma_f32_16x16x32_bf16 v[100:103], v[20:23], v[140:143], v[100:103]
	v_exp_f32_e32 v152, v152
	v_exp_f32_e32 v153, v153
	v_mfma_f32_16x16x32_bf16 v[104:107], v[20:23], v[124:127], v[104:107]
	v_exp_f32_e32 v154, v154
	v_exp_f32_e32 v155, v155
	v_mfma_f32_16x16x32_bf16 v[108:111], v[24:27], v[140:143], v[108:111]
	v_cvt_pk_bf16_f32 v148, v148, v149
	v_cvt_pk_bf16_f32 v149, v150, v151
	v_mfma_f32_16x16x32_bf16 v[112:115], v[24:27], v[124:127], v[112:115]
	v_cvt_pk_bf16_f32 v150, v152, v153
	v_cvt_pk_bf16_f32 v151, v154, v155
	v_mfma_f32_16x16x32_bf16 v[116:119], v[28:31], v[140:143], v[116:119]
	v_exp_f32_e32 v132, v132
	v_exp_f32_e32 v133, v133
	v_mfma_f32_16x16x32_bf16 v[120:123], v[28:31], v[124:127], v[120:123]
	v_exp_f32_e32 v134, v134
	v_exp_f32_e32 v135, v135
	v_mfma_f32_16x16x32_bf16 v[0:3], v[222:225], v[140:143], v[0:3]
	v_exp_f32_e32 v136, v136
	v_exp_f32_e32 v137, v137
	v_mfma_f32_16x16x32_bf16 v[4:7], v[222:225], v[124:127], v[4:7]
	v_exp_f32_e32 v138, v138
	v_exp_f32_e32 v139, v139
	s_waitcnt lgkmcnt(8)
	v_mfma_f32_16x16x32_bf16 v[92:95], v[188:191], v[148:151], v[92:95]
	v_cvt_pk_bf16_f32 v132, v132, v133
	v_cvt_pk_bf16_f32 v133, v134, v135
	v_mfma_f32_16x16x32_bf16 v[100:103], v[192:195], v[148:151], v[100:103]
	v_cvt_pk_bf16_f32 v134, v136, v137
	v_cvt_pk_bf16_f32 v135, v138, v139
	v_mfma_f32_16x16x32_bf16 v[108:111], v[196:199], v[148:151], v[108:111]
	v_mfma_f32_16x16x32_bf16 v[116:119], v[32:35], v[148:151], v[116:119]
	v_mfma_f32_16x16x32_bf16 v[0:3], v[222:225], v[148:151], v[0:3]
	v_mfma_f32_16x16x32_bf16 v[96:99], v[188:191], v[132:135], v[96:99]
	v_mfma_f32_16x16x32_bf16 v[104:107], v[192:195], v[132:135], v[104:107]
	v_mfma_f32_16x16x32_bf16 v[112:115], v[196:199], v[132:135], v[112:115]
	v_mfma_f32_16x16x32_bf16 v[120:123], v[32:35], v[132:135], v[120:123]
	v_mfma_f32_16x16x32_bf16 v[4:7], v[222:225], v[132:135], v[4:7]
	s_setprio 0
	s_setprio 1
	s_waitcnt lgkmcnt(7)
	v_mfma_f32_16x16x32_bf16 v[140:143], v[156:159], v[44:47], v[226:229]
	v_mfma_f32_16x16x32_bf16 v[124:127], v[156:159], v[56:59], v[230:233]
	s_waitcnt lgkmcnt(6)
	v_mfma_f32_16x16x32_bf16 v[144:147], v[160:163], v[44:47], v[226:229]
	v_mfma_f32_16x16x32_bf16 v[128:131], v[160:163], v[56:59], v[230:233]
	s_waitcnt lgkmcnt(5)
	v_mfma_f32_16x16x32_bf16 v[148:151], v[164:167], v[44:47], v[226:229]
	v_mfma_f32_16x16x32_bf16 v[132:135], v[164:167], v[56:59], v[230:233]
	s_waitcnt lgkmcnt(4)
	v_mfma_f32_16x16x32_bf16 v[152:155], v[168:171], v[44:47], v[226:229]
	v_mfma_f32_16x16x32_bf16 v[136:139], v[168:171], v[56:59], v[230:233]
	s_waitcnt lgkmcnt(3)
	v_mfma_f32_16x16x32_bf16 v[140:143], v[172:175], v[48:51], v[140:143]
	v_mfma_f32_16x16x32_bf16 v[124:127], v[172:175], v[60:63], v[124:127]
	ds_read_b128 v[156:159], v40 offset:16384
	ds_read_b128 v[160:163], v40 offset:20480
	ds_read_b128 v[164:167], v40 offset:24576
	ds_read_b128 v[168:171], v40 offset:28672
	s_waitcnt lgkmcnt(6)
	v_mfma_f32_16x16x32_bf16 v[144:147], v[176:179], v[48:51], v[144:147]
	v_mfma_f32_16x16x32_bf16 v[128:131], v[176:179], v[60:63], v[128:131]
	s_waitcnt lgkmcnt(5)
	v_mfma_f32_16x16x32_bf16 v[148:151], v[180:183], v[48:51], v[148:151]
	v_mfma_f32_16x16x32_bf16 v[132:135], v[180:183], v[60:63], v[132:135]
	s_waitcnt lgkmcnt(4)
	v_mfma_f32_16x16x32_bf16 v[152:155], v[184:187], v[48:51], v[152:155]
	v_mfma_f32_16x16x32_bf16 v[136:139], v[184:187], v[60:63], v[136:139]
	s_waitcnt lgkmcnt(3)
	v_mfma_f32_16x16x32_bf16 v[140:143], v[156:159], v[52:55], v[140:143]
	v_mfma_f32_16x16x32_bf16 v[124:127], v[156:159], v[64:67], v[124:127]
	s_waitcnt lgkmcnt(2)
	v_mfma_f32_16x16x32_bf16 v[144:147], v[160:163], v[52:55], v[144:147]
	v_mfma_f32_16x16x32_bf16 v[128:131], v[160:163], v[64:67], v[128:131]
	s_waitcnt lgkmcnt(1)
	v_mfma_f32_16x16x32_bf16 v[148:151], v[164:167], v[52:55], v[148:151]
	v_mfma_f32_16x16x32_bf16 v[132:135], v[164:167], v[64:67], v[132:135]
	s_waitcnt lgkmcnt(0)
	v_mfma_f32_16x16x32_bf16 v[152:155], v[168:171], v[52:55], v[152:155]
	v_mfma_f32_16x16x32_bf16 v[136:139], v[168:171], v[64:67], v[136:139]
	s_setprio 0
	ds_read_b128 v[16:19], v42 offset:8192
	ds_read_b128 v[20:23], v42 offset:10240
	ds_read_b128 v[24:27], v42 offset:12288
	ds_read_b128 v[28:31], v42 offset:14336
	v_max3_f32 v36, v140, v141, v142
	v_max3_f32 v37, v124, v125, v126
	v_max3_f32 v36, v36, v143, v144
	v_max3_f32 v37, v37, v127, v128
	v_max3_f32 v36, v36, v145, v146
	v_max3_f32 v37, v37, v129, v130
	v_max3_f32 v36, v36, v147, v148
	v_max3_f32 v37, v37, v131, v132
	v_max3_f32 v36, v36, v149, v150
	v_max3_f32 v37, v37, v133, v134
	v_max3_f32 v36, v36, v151, v152
	v_max3_f32 v37, v37, v135, v136
	v_max3_f32 v36, v36, v153, v154
	v_max3_f32 v37, v37, v137, v138
	v_max3_f32 v36, v36, v155, v155
	v_max3_f32 v37, v37, v139, v139
	v_max_f32_e32 v9, v36, v37
	v_cmp_lt_f32_e32 vcc, s44, v9
	ds_read_b128 v[188:191], v43 offset:8192
	ds_read_b128 v[192:195], v43 offset:10240
	ds_read_b128 v[196:199], v43 offset:12288
	ds_read_b128 v[32:35], v43 offset:14336
	s_cbranch_vccnz .Latt_rare_b
